# P4 epilogue hand-written: x loads 6 items ahead with counted waits, saddr addressing, deferred row reductions
# speedup vs baseline: 1.0340x; 1.0004x over previous
; __device__ __forceinline__ unsigned cvt_pk(float lo, float hi) { unsigned r; asm("v_cvt_pk_bf16_f32 %0, %1, %2" : "=v"(r) : "v"(lo), "v"(hi)); return r; }
; __device__ __forceinline__ float bflo(unsigned w) { return __uint_as_float(w << 16); }
; __device__ __forceinline__ float bfhi(unsigned w) { return __uint_as_float(w & 0xffff0000u); }
; __device__ __forceinline__ void fadd_atomic(float* p, float v) { __hip_atomic_fetch_add(p, v, __ATOMIC_RELAXED, __HIP_MEMORY_SCOPE_AGENT); }
;     __device__ __forceinline__ void operator()(const f32x4 (&acc)[2][2][4][2], const Unit& u, int wr, int wc, int fr, int fq) const {
;         int row0 = u.pm * BM + wr * 64 + fr; asm volatile("" : "+v"(row0));
; #pragma unroll
;         for (int ai = 0; ai < 2; ++ai)
; #pragma unroll
;             for (int m = 0; m < 4; ++m) { const int row = row0 + ai * HALF + m * 16; const float rb = pre[ai * 4 + m]; float q = 0.f;
; #pragma unroll
;                 for (int bj = 0; bj < 2; ++bj) { const size_t off = (size_t)row * DM + u.pn * BM + bj * HALF + wc * 32 + 8 * fq;
;                     const f32x4 x0 = *(const f32x4*)(x + off), x1 = *(const f32x4*)(x + off + 4);
;                     const f32x4 h0 = x0 + acc[ai][bj][m][0] * rb, h1 = x1 + acc[ai][bj][m][1] * rb;
;                     u32x4 w; w.x = cvt_pk(h0[0], h0[1]); w.y = cvt_pk(h0[2], h0[3]); w.z = cvt_pk(h1[0], h1[1]); w.w = cvt_pk(h1[2], h1[3]); *(u32x4*)(H1B + off) = w;
;                     u32x4 l; l.x = cvt_pk(h0[0] - bflo(w.x), h0[1] - bfhi(w.x)); l.y = cvt_pk(h0[2] - bflo(w.y), h0[3] - bfhi(w.y)); l.z = cvt_pk(h1[0] - bflo(w.z), h1[1] - bfhi(w.z)); l.w = cvt_pk(h1[2] - bflo(w.w), h1[3] - bfhi(w.w));
;                     *(u32x4*)(LO + off) = l;
;                     q += (h0[0] * h0[0] + h0[1] * h0[1]) + (h0[2] * h0[2] + h0[3] * h0[3]) + (h1[0] * h1[0] + h1[1] * h1[1]) + (h1[2] * h1[2] + h1[3] * h1[3]); }
;                 q += __shfl_xor(q, 16); q += __shfl_xor(q, 32);
;                 if (fq == 0) fadd_atomic(ss2 + row, q);
;                 asm volatile("" ::: "memory"); }
;     }
.LBB0_856:
	s_lshl_b32 s19, s48, 8
	v_or_b32_e32 v221, s19, v140
	v_lshl_add_u32 v221, v166, 10, v221
	v_lshlrev_b32_e32 v220, 2, v221
	v_lshlrev_b32_e32 v221, 1, v221
	v_lshlrev_b32_e32 v228, 2, v166
	v_xor_b32_e32 v233, 16, v159
	v_xor_b32_e32 v234, 32, v159
	v_lshlrev_b32_e32 v233, 2, v233
	v_lshlrev_b32_e32 v234, 2, v234
	v_mov_b32_e32 v230, v220
	global_load_dwordx4 v[172:175], v230, s[36:37]
	global_load_dwordx4 v[176:179], v230, s[36:37] offset:16
	global_load_dwordx4 v[180:183], v230, s[36:37] offset:512
	global_load_dwordx4 v[184:187], v230, s[36:37] offset:528
	v_add_u32_e32 v230, 0x10000, v220
	global_load_dwordx4 v[188:191], v230, s[36:37]
	global_load_dwordx4 v[192:195], v230, s[36:37] offset:16
	global_load_dwordx4 v[196:199], v230, s[36:37] offset:512
	global_load_dwordx4 v[200:203], v230, s[36:37] offset:528
	v_add_u32_e32 v230, 0x20000, v220
	global_load_dwordx4 v[204:207], v230, s[36:37]
	global_load_dwordx4 v[208:211], v230, s[36:37] offset:16
	global_load_dwordx4 v[212:215], v230, s[36:37] offset:512
	global_load_dwordx4 v[216:219], v230, s[36:37] offset:528
	s_waitcnt vmcnt(10)
	v_pk_fma_f32 v[174:175], v[130:131], v[150:151], v[174:175] op_sel_hi:[1,0,1]
	v_pk_fma_f32 v[172:173], v[128:129], v[150:151], v[172:173] op_sel_hi:[1,0,1]
	v_pk_fma_f32 v[178:179], v[126:127], v[150:151], v[178:179] op_sel_hi:[1,0,1]
	v_pk_fma_f32 v[176:177], v[124:125], v[150:151], v[176:177] op_sel_hi:[1,0,1]
	v_mov_b32_e32 v231, v221
	v_cvt_pk_bf16_f32 v128, v172, v173
	v_cvt_pk_bf16_f32 v129, v174, v175
	v_cvt_pk_bf16_f32 v130, v176, v177
	v_cvt_pk_bf16_f32 v131, v178, v179
	global_store_dwordx4 v231, v[128:131], s[12:13]
	v_mul_f32_e32 v222, v172, v172
	v_fmac_f32_e32 v222, v173, v173
	v_fmac_f32_e32 v222, v174, v174
	v_fmac_f32_e32 v222, v175, v175
	v_fmac_f32_e32 v222, v176, v176
	v_fmac_f32_e32 v222, v177, v177
	v_fmac_f32_e32 v222, v178, v178
	v_fmac_f32_e32 v222, v179, v179
	v_lshlrev_b32_e32 v224, 16, v128
	v_and_b32_e32 v225, 0xffff0000, v128
	v_sub_f32_e32 v224, v172, v224
	v_sub_f32_e32 v225, v173, v225
	v_cvt_pk_bf16_f32 v124, v224, v225
	v_lshlrev_b32_e32 v226, 16, v129
	v_and_b32_e32 v227, 0xffff0000, v129
	v_sub_f32_e32 v226, v174, v226
	v_sub_f32_e32 v227, v175, v227
	v_cvt_pk_bf16_f32 v125, v226, v227
	v_lshlrev_b32_e32 v224, 16, v130
	v_and_b32_e32 v225, 0xffff0000, v130
	v_sub_f32_e32 v224, v176, v224
	v_sub_f32_e32 v225, v177, v225
	v_cvt_pk_bf16_f32 v126, v224, v225
	v_lshlrev_b32_e32 v226, 16, v131
	v_and_b32_e32 v227, 0xffff0000, v131
	v_sub_f32_e32 v226, v178, v226
	v_sub_f32_e32 v227, v179, v227
	v_cvt_pk_bf16_f32 v127, v226, v227
	global_store_dwordx4 v231, v[124:127], s[10:11]
	v_add_u32_e32 v230, 0x30000, v220
	global_load_dwordx4 v[172:175], v230, s[36:37]
	global_load_dwordx4 v[176:179], v230, s[36:37] offset:16
	s_waitcnt vmcnt(12)
	v_pk_fma_f32 v[182:183], v[122:123], v[150:151], v[182:183] op_sel_hi:[1,0,1]
	v_pk_fma_f32 v[180:181], v[120:121], v[150:151], v[180:181] op_sel_hi:[1,0,1]
	v_pk_fma_f32 v[186:187], v[118:119], v[150:151], v[186:187] op_sel_hi:[1,0,1]
	v_pk_fma_f32 v[184:185], v[116:117], v[150:151], v[184:185] op_sel_hi:[1,0,1]
	v_cvt_pk_bf16_f32 v120, v180, v181
	v_cvt_pk_bf16_f32 v121, v182, v183
	v_cvt_pk_bf16_f32 v122, v184, v185
	v_cvt_pk_bf16_f32 v123, v186, v187
	global_store_dwordx4 v231, v[120:123], s[12:13] offset:256
	v_fmac_f32_e32 v222, v180, v180
	v_fmac_f32_e32 v222, v181, v181
	v_fmac_f32_e32 v222, v182, v182
	v_fmac_f32_e32 v222, v183, v183
	v_fmac_f32_e32 v222, v184, v184
	v_fmac_f32_e32 v222, v185, v185
	v_fmac_f32_e32 v222, v186, v186
	v_fmac_f32_e32 v222, v187, v187
	v_lshlrev_b32_e32 v224, 16, v120
	v_and_b32_e32 v225, 0xffff0000, v120
	v_sub_f32_e32 v224, v180, v224
	v_sub_f32_e32 v225, v181, v225
	v_cvt_pk_bf16_f32 v116, v224, v225
	v_lshlrev_b32_e32 v226, 16, v121
	v_and_b32_e32 v227, 0xffff0000, v121
	v_sub_f32_e32 v226, v182, v226
	v_sub_f32_e32 v227, v183, v227
	v_cvt_pk_bf16_f32 v117, v226, v227
	v_lshlrev_b32_e32 v224, 16, v122
	v_and_b32_e32 v225, 0xffff0000, v122
	v_sub_f32_e32 v224, v184, v224
	v_sub_f32_e32 v225, v185, v225
	v_cvt_pk_bf16_f32 v118, v224, v225
	v_lshlrev_b32_e32 v226, 16, v123
	v_and_b32_e32 v227, 0xffff0000, v123
	v_sub_f32_e32 v226, v186, v226
	v_sub_f32_e32 v227, v187, v227
	v_cvt_pk_bf16_f32 v119, v226, v227
	global_store_dwordx4 v231, v[116:119], s[10:11] offset:256
	global_load_dwordx4 v[180:183], v230, s[36:37] offset:512
	global_load_dwordx4 v[184:187], v230, s[36:37] offset:528
	ds_bpermute_b32 v229, v233, v222
	s_waitcnt vmcnt(14)
	v_pk_fma_f32 v[190:191], v[114:115], v[154:155], v[190:191] op_sel_hi:[1,0,1]
	v_pk_fma_f32 v[188:189], v[112:113], v[154:155], v[188:189] op_sel_hi:[1,0,1]
	v_pk_fma_f32 v[194:195], v[110:111], v[154:155], v[194:195] op_sel_hi:[1,0,1]
	v_pk_fma_f32 v[192:193], v[108:109], v[154:155], v[192:193] op_sel_hi:[1,0,1]
	v_add_u32_e32 v231, 0x8000, v221
	v_cvt_pk_bf16_f32 v112, v188, v189
	v_cvt_pk_bf16_f32 v113, v190, v191
	v_cvt_pk_bf16_f32 v114, v192, v193
	v_cvt_pk_bf16_f32 v115, v194, v195
	global_store_dwordx4 v231, v[112:115], s[12:13]
	v_mul_f32_e32 v223, v188, v188
	v_fmac_f32_e32 v223, v189, v189
	v_fmac_f32_e32 v223, v190, v190
	v_fmac_f32_e32 v223, v191, v191
	v_fmac_f32_e32 v223, v192, v192
	v_fmac_f32_e32 v223, v193, v193
	v_fmac_f32_e32 v223, v194, v194
	v_fmac_f32_e32 v223, v195, v195
	v_lshlrev_b32_e32 v224, 16, v112
	v_and_b32_e32 v225, 0xffff0000, v112
	v_sub_f32_e32 v224, v188, v224
	v_sub_f32_e32 v225, v189, v225
	v_cvt_pk_bf16_f32 v108, v224, v225
	v_lshlrev_b32_e32 v226, 16, v113
	v_and_b32_e32 v227, 0xffff0000, v113
	v_sub_f32_e32 v226, v190, v226
	v_sub_f32_e32 v227, v191, v227
	v_cvt_pk_bf16_f32 v109, v226, v227
	v_lshlrev_b32_e32 v224, 16, v114
	v_and_b32_e32 v225, 0xffff0000, v114
	v_sub_f32_e32 v224, v192, v224
	v_sub_f32_e32 v225, v193, v225
	v_cvt_pk_bf16_f32 v110, v224, v225
	v_lshlrev_b32_e32 v226, 16, v115
	v_and_b32_e32 v227, 0xffff0000, v115
	v_sub_f32_e32 v226, v194, v226
	v_sub_f32_e32 v227, v195, v227
	v_cvt_pk_bf16_f32 v111, v226, v227
	global_store_dwordx4 v231, v[108:111], s[10:11]
	v_add_u32_e32 v230, 0x80000, v220
	global_load_dwordx4 v[188:191], v230, s[36:37]
	global_load_dwordx4 v[192:195], v230, s[36:37] offset:16
	s_waitcnt lgkmcnt(0)
; __device__ __forceinline__ unsigned cvt_pk(float lo, float hi) { unsigned r; asm("v_cvt_pk_bf16_f32 %0, %1, %2" : "=v"(r) : "v"(lo), "v"(hi)); return r; }
; __device__ __forceinline__ float bflo(unsigned w) { return __uint_as_float(w << 16); }
; __device__ __forceinline__ float bfhi(unsigned w) { return __uint_as_float(w & 0xffff0000u); }
; __device__ __forceinline__ void fadd_atomic(float* p, float v) { __hip_atomic_fetch_add(p, v, __ATOMIC_RELAXED, __HIP_MEMORY_SCOPE_AGENT); }
;     __device__ __forceinline__ void operator()(const f32x4 (&acc)[2][2][4][2], const Unit& u, int wr, int wc, int fr, int fq) const {
;         int row0 = u.pm * BM + wr * 64 + fr; asm volatile("" : "+v"(row0));
; #pragma unroll
;         for (int ai = 0; ai < 2; ++ai)
; #pragma unroll
;             for (int m = 0; m < 4; ++m) { const int row = row0 + ai * HALF + m * 16; const float rb = pre[ai * 4 + m]; float q = 0.f;
; #pragma unroll
;                 for (int bj = 0; bj < 2; ++bj) { const size_t off = (size_t)row * DM + u.pn * BM + bj * HALF + wc * 32 + 8 * fq;
;                     const f32x4 x0 = *(const f32x4*)(x + off), x1 = *(const f32x4*)(x + off + 4);
;                     const f32x4 h0 = x0 + acc[ai][bj][m][0] * rb, h1 = x1 + acc[ai][bj][m][1] * rb;
;                     u32x4 w; w.x = cvt_pk(h0[0], h0[1]); w.y = cvt_pk(h0[2], h0[3]); w.z = cvt_pk(h1[0], h1[1]); w.w = cvt_pk(h1[2], h1[3]); *(u32x4*)(H1B + off) = w;
;                     u32x4 l; l.x = cvt_pk(h0[0] - bflo(w.x), h0[1] - bfhi(w.x)); l.y = cvt_pk(h0[2] - bflo(w.y), h0[3] - bfhi(w.y)); l.z = cvt_pk(h1[0] - bflo(w.z), h1[1] - bfhi(w.z)); l.w = cvt_pk(h1[2] - bflo(w.w), h1[3] - bfhi(w.w));
;                     *(u32x4*)(LO + off) = l;
;                     q += (h0[0] * h0[0] + h0[1] * h0[1]) + (h0[2] * h0[2] + h0[3] * h0[3]) + (h1[0] * h1[0] + h1[1] * h1[1]) + (h1[2] * h1[2] + h1[3] * h1[3]); }
;                 q += __shfl_xor(q, 16); q += __shfl_xor(q, 32);
;                 if (fq == 0) fadd_atomic(ss2 + row, q);
;                 asm volatile("" ::: "memory"); }
;     }
	v_add_f32_e32 v222, v222, v229
	ds_bpermute_b32 v229, v234, v222
	s_waitcnt vmcnt(16)
	v_pk_fma_f32 v[198:199], v[106:107], v[154:155], v[198:199] op_sel_hi:[1,0,1]
	v_pk_fma_f32 v[196:197], v[104:105], v[154:155], v[196:197] op_sel_hi:[1,0,1]
	v_pk_fma_f32 v[202:203], v[102:103], v[154:155], v[202:203] op_sel_hi:[1,0,1]
	v_pk_fma_f32 v[200:201], v[100:101], v[154:155], v[200:201] op_sel_hi:[1,0,1]
	v_cvt_pk_bf16_f32 v104, v196, v197
	v_cvt_pk_bf16_f32 v105, v198, v199
	v_cvt_pk_bf16_f32 v106, v200, v201
	v_cvt_pk_bf16_f32 v107, v202, v203
	global_store_dwordx4 v231, v[104:107], s[12:13] offset:256
	v_fmac_f32_e32 v223, v196, v196
	v_fmac_f32_e32 v223, v197, v197
	v_fmac_f32_e32 v223, v198, v198
	v_fmac_f32_e32 v223, v199, v199
	v_fmac_f32_e32 v223, v200, v200
	v_fmac_f32_e32 v223, v201, v201
	v_fmac_f32_e32 v223, v202, v202
	v_fmac_f32_e32 v223, v203, v203
	v_lshlrev_b32_e32 v224, 16, v104
	v_and_b32_e32 v225, 0xffff0000, v104
	v_sub_f32_e32 v224, v196, v224
	v_sub_f32_e32 v225, v197, v225
	v_cvt_pk_bf16_f32 v100, v224, v225
	v_lshlrev_b32_e32 v226, 16, v105
	v_and_b32_e32 v227, 0xffff0000, v105
	v_sub_f32_e32 v226, v198, v226
	v_sub_f32_e32 v227, v199, v227
	v_cvt_pk_bf16_f32 v101, v226, v227
	v_lshlrev_b32_e32 v224, 16, v106
	v_and_b32_e32 v225, 0xffff0000, v106
	v_sub_f32_e32 v224, v200, v224
	v_sub_f32_e32 v225, v201, v225
	v_cvt_pk_bf16_f32 v102, v224, v225
	v_lshlrev_b32_e32 v226, 16, v107
	v_and_b32_e32 v227, 0xffff0000, v107
	v_sub_f32_e32 v226, v202, v226
	v_sub_f32_e32 v227, v203, v227
	v_cvt_pk_bf16_f32 v103, v226, v227
	global_store_dwordx4 v231, v[100:103], s[10:11] offset:256
	global_load_dwordx4 v[196:199], v230, s[36:37] offset:512
	global_load_dwordx4 v[200:203], v230, s[36:37] offset:528
	s_waitcnt lgkmcnt(0)
	v_add_f32_e32 v222, v222, v229
	v_mov_b32_e32 v232, v228
	s_and_saveexec_b64 s[48:49], s[2:3]
	global_atomic_add_f32 v232, v222, s[30:31]
	s_or_b64 exec, exec, s[48:49]
	ds_bpermute_b32 v229, v233, v223
	s_waitcnt vmcnt(19)
	v_pk_fma_f32 v[206:207], v[98:99], v[152:153], v[206:207] op_sel_hi:[1,0,1]
	v_pk_fma_f32 v[204:205], v[96:97], v[152:153], v[204:205] op_sel_hi:[1,0,1]
	v_pk_fma_f32 v[210:211], v[94:95], v[152:153], v[210:211] op_sel_hi:[1,0,1]
	v_pk_fma_f32 v[208:209], v[92:93], v[152:153], v[208:209] op_sel_hi:[1,0,1]
	v_add_u32_e32 v231, 0x10000, v221
	v_cvt_pk_bf16_f32 v96, v204, v205
	v_cvt_pk_bf16_f32 v97, v206, v207
	v_cvt_pk_bf16_f32 v98, v208, v209
	v_cvt_pk_bf16_f32 v99, v210, v211
	global_store_dwordx4 v231, v[96:99], s[12:13]
	v_mul_f32_e32 v222, v204, v204
	v_fmac_f32_e32 v222, v205, v205
	v_fmac_f32_e32 v222, v206, v206
	v_fmac_f32_e32 v222, v207, v207
	v_fmac_f32_e32 v222, v208, v208
	v_fmac_f32_e32 v222, v209, v209
	v_fmac_f32_e32 v222, v210, v210
	v_fmac_f32_e32 v222, v211, v211
	v_lshlrev_b32_e32 v224, 16, v96
	v_and_b32_e32 v225, 0xffff0000, v96
	v_sub_f32_e32 v224, v204, v224
	v_sub_f32_e32 v225, v205, v225
	v_cvt_pk_bf16_f32 v92, v224, v225
	v_lshlrev_b32_e32 v226, 16, v97
	v_and_b32_e32 v227, 0xffff0000, v97
	v_sub_f32_e32 v226, v206, v226
	v_sub_f32_e32 v227, v207, v227
	v_cvt_pk_bf16_f32 v93, v226, v227
	v_lshlrev_b32_e32 v224, 16, v98
	v_and_b32_e32 v225, 0xffff0000, v98
	v_sub_f32_e32 v224, v208, v224
	v_sub_f32_e32 v225, v209, v225
	v_cvt_pk_bf16_f32 v94, v224, v225
	v_lshlrev_b32_e32 v226, 16, v99
	v_and_b32_e32 v227, 0xffff0000, v99
	v_sub_f32_e32 v226, v210, v226
	v_sub_f32_e32 v227, v211, v227
	v_cvt_pk_bf16_f32 v95, v226, v227
	global_store_dwordx4 v231, v[92:95], s[10:11]
	v_add_u32_e32 v230, 0x90000, v220
	global_load_dwordx4 v[204:207], v230, s[36:37]
	global_load_dwordx4 v[208:211], v230, s[36:37] offset:16
	s_waitcnt lgkmcnt(0)
	v_add_f32_e32 v223, v223, v229
	ds_bpermute_b32 v229, v234, v223
	s_waitcnt vmcnt(21)
	v_pk_fma_f32 v[214:215], v[90:91], v[152:153], v[214:215] op_sel_hi:[1,0,1]
	v_pk_fma_f32 v[212:213], v[88:89], v[152:153], v[212:213] op_sel_hi:[1,0,1]
	v_pk_fma_f32 v[218:219], v[86:87], v[152:153], v[218:219] op_sel_hi:[1,0,1]
	v_pk_fma_f32 v[216:217], v[84:85], v[152:153], v[216:217] op_sel_hi:[1,0,1]
	v_cvt_pk_bf16_f32 v88, v212, v213
	v_cvt_pk_bf16_f32 v89, v214, v215
	v_cvt_pk_bf16_f32 v90, v216, v217
	v_cvt_pk_bf16_f32 v91, v218, v219
	global_store_dwordx4 v231, v[88:91], s[12:13] offset:256
	v_fmac_f32_e32 v222, v212, v212
	v_fmac_f32_e32 v222, v213, v213
	v_fmac_f32_e32 v222, v214, v214
	v_fmac_f32_e32 v222, v215, v215
	v_fmac_f32_e32 v222, v216, v216
	v_fmac_f32_e32 v222, v217, v217
	v_fmac_f32_e32 v222, v218, v218
	v_fmac_f32_e32 v222, v219, v219
	v_lshlrev_b32_e32 v224, 16, v88
	v_and_b32_e32 v225, 0xffff0000, v88
	v_sub_f32_e32 v224, v212, v224
	v_sub_f32_e32 v225, v213, v225
	v_cvt_pk_bf16_f32 v84, v224, v225
	v_lshlrev_b32_e32 v226, 16, v89
	v_and_b32_e32 v227, 0xffff0000, v89
	v_sub_f32_e32 v226, v214, v226
	v_sub_f32_e32 v227, v215, v227
	v_cvt_pk_bf16_f32 v85, v226, v227
	v_lshlrev_b32_e32 v224, 16, v90
	v_and_b32_e32 v225, 0xffff0000, v90
	v_sub_f32_e32 v224, v216, v224
	v_sub_f32_e32 v225, v217, v225
	v_cvt_pk_bf16_f32 v86, v224, v225
	v_lshlrev_b32_e32 v226, 16, v91
	v_and_b32_e32 v227, 0xffff0000, v91
	v_sub_f32_e32 v226, v218, v226
	v_sub_f32_e32 v227, v219, v227
	v_cvt_pk_bf16_f32 v87, v226, v227
	global_store_dwordx4 v231, v[84:87], s[10:11] offset:256
	global_load_dwordx4 v[212:215], v230, s[36:37] offset:512
	global_load_dwordx4 v[216:219], v230, s[36:37] offset:528
	s_waitcnt lgkmcnt(0)
	v_add_f32_e32 v223, v223, v229
	v_add_u32_e32 v232, 0x40, v228
	s_and_saveexec_b64 s[48:49], s[2:3]
	global_atomic_add_f32 v232, v223, s[30:31]
	s_or_b64 exec, exec, s[48:49]
	ds_bpermute_b32 v229, v233, v222
	s_waitcnt vmcnt(22)
; __device__ __forceinline__ unsigned cvt_pk(float lo, float hi) { unsigned r; asm("v_cvt_pk_bf16_f32 %0, %1, %2" : "=v"(r) : "v"(lo), "v"(hi)); return r; }
; __device__ __forceinline__ float bflo(unsigned w) { return __uint_as_float(w << 16); }
; __device__ __forceinline__ float bfhi(unsigned w) { return __uint_as_float(w & 0xffff0000u); }
; __device__ __forceinline__ void fadd_atomic(float* p, float v) { __hip_atomic_fetch_add(p, v, __ATOMIC_RELAXED, __HIP_MEMORY_SCOPE_AGENT); }
;     __device__ __forceinline__ void operator()(const f32x4 (&acc)[2][2][4][2], const Unit& u, int wr, int wc, int fr, int fq) const {
;         int row0 = u.pm * BM + wr * 64 + fr; asm volatile("" : "+v"(row0));
; #pragma unroll
;         for (int ai = 0; ai < 2; ++ai)
; #pragma unroll
;             for (int m = 0; m < 4; ++m) { const int row = row0 + ai * HALF + m * 16; const float rb = pre[ai * 4 + m]; float q = 0.f;
; #pragma unroll
;                 for (int bj = 0; bj < 2; ++bj) { const size_t off = (size_t)row * DM + u.pn * BM + bj * HALF + wc * 32 + 8 * fq;
;                     const f32x4 x0 = *(const f32x4*)(x + off), x1 = *(const f32x4*)(x + off + 4);
;                     const f32x4 h0 = x0 + acc[ai][bj][m][0] * rb, h1 = x1 + acc[ai][bj][m][1] * rb;
;                     u32x4 w; w.x = cvt_pk(h0[0], h0[1]); w.y = cvt_pk(h0[2], h0[3]); w.z = cvt_pk(h1[0], h1[1]); w.w = cvt_pk(h1[2], h1[3]); *(u32x4*)(H1B + off) = w;
;                     u32x4 l; l.x = cvt_pk(h0[0] - bflo(w.x), h0[1] - bfhi(w.x)); l.y = cvt_pk(h0[2] - bflo(w.y), h0[3] - bfhi(w.y)); l.z = cvt_pk(h1[0] - bflo(w.z), h1[1] - bfhi(w.z)); l.w = cvt_pk(h1[2] - bflo(w.w), h1[3] - bfhi(w.w));
;                     *(u32x4*)(LO + off) = l;
;                     q += (h0[0] * h0[0] + h0[1] * h0[1]) + (h0[2] * h0[2] + h0[3] * h0[3]) + (h1[0] * h1[0] + h1[1] * h1[1]) + (h1[2] * h1[2] + h1[3] * h1[3]); }
;                 q += __shfl_xor(q, 16); q += __shfl_xor(q, 32);
;                 if (fq == 0) fadd_atomic(ss2 + row, q);
;                 asm volatile("" ::: "memory"); }
;     }
	v_pk_fma_f32 v[174:175], v[82:83], v[156:157], v[174:175] op_sel_hi:[1,0,1]
	v_pk_fma_f32 v[172:173], v[80:81], v[156:157], v[172:173] op_sel_hi:[1,0,1]
	v_pk_fma_f32 v[178:179], v[78:79], v[156:157], v[178:179] op_sel_hi:[1,0,1]
	v_pk_fma_f32 v[176:177], v[76:77], v[156:157], v[176:177] op_sel_hi:[1,0,1]
	v_add_u32_e32 v231, 0x18000, v221
	v_cvt_pk_bf16_f32 v80, v172, v173
	v_cvt_pk_bf16_f32 v81, v174, v175
	v_cvt_pk_bf16_f32 v82, v176, v177
	v_cvt_pk_bf16_f32 v83, v178, v179
	global_store_dwordx4 v231, v[80:83], s[12:13]
	v_mul_f32_e32 v223, v172, v172
	v_fmac_f32_e32 v223, v173, v173
	v_fmac_f32_e32 v223, v174, v174
	v_fmac_f32_e32 v223, v175, v175
	v_fmac_f32_e32 v223, v176, v176
	v_fmac_f32_e32 v223, v177, v177
	v_fmac_f32_e32 v223, v178, v178
	v_fmac_f32_e32 v223, v179, v179
	v_lshlrev_b32_e32 v224, 16, v80
	v_and_b32_e32 v225, 0xffff0000, v80
	v_sub_f32_e32 v224, v172, v224
	v_sub_f32_e32 v225, v173, v225
	v_cvt_pk_bf16_f32 v76, v224, v225
	v_lshlrev_b32_e32 v226, 16, v81
	v_and_b32_e32 v227, 0xffff0000, v81
	v_sub_f32_e32 v226, v174, v226
	v_sub_f32_e32 v227, v175, v227
	v_cvt_pk_bf16_f32 v77, v226, v227
	v_lshlrev_b32_e32 v224, 16, v82
	v_and_b32_e32 v225, 0xffff0000, v82
	v_sub_f32_e32 v224, v176, v224
	v_sub_f32_e32 v225, v177, v225
	v_cvt_pk_bf16_f32 v78, v224, v225
	v_lshlrev_b32_e32 v226, 16, v83
	v_and_b32_e32 v227, 0xffff0000, v83
	v_sub_f32_e32 v226, v178, v226
	v_sub_f32_e32 v227, v179, v227
	v_cvt_pk_bf16_f32 v79, v226, v227
	global_store_dwordx4 v231, v[76:79], s[10:11]
	v_add_u32_e32 v230, 0xa0000, v220
	global_load_dwordx4 v[172:175], v230, s[36:37]
	global_load_dwordx4 v[176:179], v230, s[36:37] offset:16
	s_waitcnt lgkmcnt(0)
	v_add_f32_e32 v222, v222, v229
	ds_bpermute_b32 v229, v234, v222
	s_waitcnt vmcnt(22)
	v_pk_fma_f32 v[182:183], v[74:75], v[156:157], v[182:183] op_sel_hi:[1,0,1]
	v_pk_fma_f32 v[180:181], v[72:73], v[156:157], v[180:181] op_sel_hi:[1,0,1]
	v_pk_fma_f32 v[186:187], v[70:71], v[156:157], v[186:187] op_sel_hi:[1,0,1]
	v_pk_fma_f32 v[184:185], v[68:69], v[156:157], v[184:185] op_sel_hi:[1,0,1]
	v_cvt_pk_bf16_f32 v72, v180, v181
	v_cvt_pk_bf16_f32 v73, v182, v183
	v_cvt_pk_bf16_f32 v74, v184, v185
	v_cvt_pk_bf16_f32 v75, v186, v187
	global_store_dwordx4 v231, v[72:75], s[12:13] offset:256
	v_fmac_f32_e32 v223, v180, v180
	v_fmac_f32_e32 v223, v181, v181
	v_fmac_f32_e32 v223, v182, v182
	v_fmac_f32_e32 v223, v183, v183
	v_fmac_f32_e32 v223, v184, v184
	v_fmac_f32_e32 v223, v185, v185
	v_fmac_f32_e32 v223, v186, v186
	v_fmac_f32_e32 v223, v187, v187
	v_lshlrev_b32_e32 v224, 16, v72
	v_and_b32_e32 v225, 0xffff0000, v72
	v_sub_f32_e32 v224, v180, v224
	v_sub_f32_e32 v225, v181, v225
	v_cvt_pk_bf16_f32 v68, v224, v225
	v_lshlrev_b32_e32 v226, 16, v73
	v_and_b32_e32 v227, 0xffff0000, v73
	v_sub_f32_e32 v226, v182, v226
	v_sub_f32_e32 v227, v183, v227
	v_cvt_pk_bf16_f32 v69, v226, v227
	v_lshlrev_b32_e32 v224, 16, v74
	v_and_b32_e32 v225, 0xffff0000, v74
	v_sub_f32_e32 v224, v184, v224
	v_sub_f32_e32 v225, v185, v225
	v_cvt_pk_bf16_f32 v70, v224, v225
	v_lshlrev_b32_e32 v226, 16, v75
	v_and_b32_e32 v227, 0xffff0000, v75
	v_sub_f32_e32 v226, v186, v226
	v_sub_f32_e32 v227, v187, v227
	v_cvt_pk_bf16_f32 v71, v226, v227
	global_store_dwordx4 v231, v[68:71], s[10:11] offset:256
	global_load_dwordx4 v[180:183], v230, s[36:37] offset:512
	global_load_dwordx4 v[184:187], v230, s[36:37] offset:528
	s_waitcnt lgkmcnt(0)
	v_add_f32_e32 v222, v222, v229
	v_add_u32_e32 v232, 0x80, v228
	s_and_saveexec_b64 s[48:49], s[2:3]
	global_atomic_add_f32 v232, v222, s[30:31]
	s_or_b64 exec, exec, s[48:49]
	ds_bpermute_b32 v229, v233, v223
	s_waitcnt vmcnt(23)
	v_pk_fma_f32 v[190:191], v[66:67], v[158:159], v[190:191] op_sel_hi:[1,0,1]
	v_pk_fma_f32 v[188:189], v[64:65], v[158:159], v[188:189] op_sel_hi:[1,0,1]
	v_pk_fma_f32 v[194:195], v[62:63], v[158:159], v[194:195] op_sel_hi:[1,0,1]
	v_pk_fma_f32 v[192:193], v[60:61], v[158:159], v[192:193] op_sel_hi:[1,0,1]
	v_add_u32_e32 v231, 0x40000, v221
	v_cvt_pk_bf16_f32 v64, v188, v189
	v_cvt_pk_bf16_f32 v65, v190, v191
	v_cvt_pk_bf16_f32 v66, v192, v193
	v_cvt_pk_bf16_f32 v67, v194, v195
	global_store_dwordx4 v231, v[64:67], s[12:13]
	v_mul_f32_e32 v222, v188, v188
	v_fmac_f32_e32 v222, v189, v189
	v_fmac_f32_e32 v222, v190, v190
	v_fmac_f32_e32 v222, v191, v191
	v_fmac_f32_e32 v222, v192, v192
	v_fmac_f32_e32 v222, v193, v193
	v_fmac_f32_e32 v222, v194, v194
	v_fmac_f32_e32 v222, v195, v195
	v_lshlrev_b32_e32 v224, 16, v64
	v_and_b32_e32 v225, 0xffff0000, v64
	v_sub_f32_e32 v224, v188, v224
	v_sub_f32_e32 v225, v189, v225
	v_cvt_pk_bf16_f32 v60, v224, v225
	v_lshlrev_b32_e32 v226, 16, v65
	v_and_b32_e32 v227, 0xffff0000, v65
	v_sub_f32_e32 v226, v190, v226
	v_sub_f32_e32 v227, v191, v227
	v_cvt_pk_bf16_f32 v61, v226, v227
	v_lshlrev_b32_e32 v224, 16, v66
	v_and_b32_e32 v225, 0xffff0000, v66
	v_sub_f32_e32 v224, v192, v224
	v_sub_f32_e32 v225, v193, v225
	v_cvt_pk_bf16_f32 v62, v224, v225
	v_lshlrev_b32_e32 v226, 16, v67
	v_and_b32_e32 v227, 0xffff0000, v67
	v_sub_f32_e32 v226, v194, v226
	v_sub_f32_e32 v227, v195, v227
	v_cvt_pk_bf16_f32 v63, v226, v227
	global_store_dwordx4 v231, v[60:63], s[10:11]
	v_add_u32_e32 v230, 0xb0000, v220
	global_load_dwordx4 v[188:191], v230, s[36:37]
	global_load_dwordx4 v[192:195], v230, s[36:37] offset:16
	s_waitcnt lgkmcnt(0)
	v_add_f32_e32 v223, v223, v229
	ds_bpermute_b32 v229, v234, v223
	s_waitcnt vmcnt(23)
; __device__ __forceinline__ unsigned cvt_pk(float lo, float hi) { unsigned r; asm("v_cvt_pk_bf16_f32 %0, %1, %2" : "=v"(r) : "v"(lo), "v"(hi)); return r; }
; __device__ __forceinline__ float bflo(unsigned w) { return __uint_as_float(w << 16); }
; __device__ __forceinline__ float bfhi(unsigned w) { return __uint_as_float(w & 0xffff0000u); }
; __device__ __forceinline__ void fadd_atomic(float* p, float v) { __hip_atomic_fetch_add(p, v, __ATOMIC_RELAXED, __HIP_MEMORY_SCOPE_AGENT); }
;     __device__ __forceinline__ void operator()(const f32x4 (&acc)[2][2][4][2], const Unit& u, int wr, int wc, int fr, int fq) const {
;         int row0 = u.pm * BM + wr * 64 + fr; asm volatile("" : "+v"(row0));
; #pragma unroll
;         for (int ai = 0; ai < 2; ++ai)
; #pragma unroll
;             for (int m = 0; m < 4; ++m) { const int row = row0 + ai * HALF + m * 16; const float rb = pre[ai * 4 + m]; float q = 0.f;
; #pragma unroll
;                 for (int bj = 0; bj < 2; ++bj) { const size_t off = (size_t)row * DM + u.pn * BM + bj * HALF + wc * 32 + 8 * fq;
;                     const f32x4 x0 = *(const f32x4*)(x + off), x1 = *(const f32x4*)(x + off + 4);
;                     const f32x4 h0 = x0 + acc[ai][bj][m][0] * rb, h1 = x1 + acc[ai][bj][m][1] * rb;
;                     u32x4 w; w.x = cvt_pk(h0[0], h0[1]); w.y = cvt_pk(h0[2], h0[3]); w.z = cvt_pk(h1[0], h1[1]); w.w = cvt_pk(h1[2], h1[3]); *(u32x4*)(H1B + off) = w;
;                     u32x4 l; l.x = cvt_pk(h0[0] - bflo(w.x), h0[1] - bfhi(w.x)); l.y = cvt_pk(h0[2] - bflo(w.y), h0[3] - bfhi(w.y)); l.z = cvt_pk(h1[0] - bflo(w.z), h1[1] - bfhi(w.z)); l.w = cvt_pk(h1[2] - bflo(w.w), h1[3] - bfhi(w.w));
;                     *(u32x4*)(LO + off) = l;
;                     q += (h0[0] * h0[0] + h0[1] * h0[1]) + (h0[2] * h0[2] + h0[3] * h0[3]) + (h1[0] * h1[0] + h1[1] * h1[1]) + (h1[2] * h1[2] + h1[3] * h1[3]); }
;                 q += __shfl_xor(q, 16); q += __shfl_xor(q, 32);
;                 if (fq == 0) fadd_atomic(ss2 + row, q);
;                 asm volatile("" ::: "memory"); }
;     }
	v_pk_fma_f32 v[198:199], v[58:59], v[158:159], v[198:199] op_sel_hi:[1,0,1]
	v_pk_fma_f32 v[196:197], v[56:57], v[158:159], v[196:197] op_sel_hi:[1,0,1]
	v_pk_fma_f32 v[202:203], v[54:55], v[158:159], v[202:203] op_sel_hi:[1,0,1]
	v_pk_fma_f32 v[200:201], v[52:53], v[158:159], v[200:201] op_sel_hi:[1,0,1]
	v_cvt_pk_bf16_f32 v56, v196, v197
	v_cvt_pk_bf16_f32 v57, v198, v199
	v_cvt_pk_bf16_f32 v58, v200, v201
	v_cvt_pk_bf16_f32 v59, v202, v203
	global_store_dwordx4 v231, v[56:59], s[12:13] offset:256
	v_fmac_f32_e32 v222, v196, v196
	v_fmac_f32_e32 v222, v197, v197
	v_fmac_f32_e32 v222, v198, v198
	v_fmac_f32_e32 v222, v199, v199
	v_fmac_f32_e32 v222, v200, v200
	v_fmac_f32_e32 v222, v201, v201
	v_fmac_f32_e32 v222, v202, v202
	v_fmac_f32_e32 v222, v203, v203
	v_lshlrev_b32_e32 v224, 16, v56
	v_and_b32_e32 v225, 0xffff0000, v56
	v_sub_f32_e32 v224, v196, v224
	v_sub_f32_e32 v225, v197, v225
	v_cvt_pk_bf16_f32 v52, v224, v225
	v_lshlrev_b32_e32 v226, 16, v57
	v_and_b32_e32 v227, 0xffff0000, v57
	v_sub_f32_e32 v226, v198, v226
	v_sub_f32_e32 v227, v199, v227
	v_cvt_pk_bf16_f32 v53, v226, v227
	v_lshlrev_b32_e32 v224, 16, v58
	v_and_b32_e32 v225, 0xffff0000, v58
	v_sub_f32_e32 v224, v200, v224
	v_sub_f32_e32 v225, v201, v225
	v_cvt_pk_bf16_f32 v54, v224, v225
	v_lshlrev_b32_e32 v226, 16, v59
	v_and_b32_e32 v227, 0xffff0000, v59
	v_sub_f32_e32 v226, v202, v226
	v_sub_f32_e32 v227, v203, v227
	v_cvt_pk_bf16_f32 v55, v226, v227
	global_store_dwordx4 v231, v[52:55], s[10:11] offset:256
	global_load_dwordx4 v[196:199], v230, s[36:37] offset:512
	global_load_dwordx4 v[200:203], v230, s[36:37] offset:528
	s_waitcnt lgkmcnt(0)
	v_add_f32_e32 v223, v223, v229
	v_add_u32_e32 v232, 0xc0, v228
	s_and_saveexec_b64 s[48:49], s[2:3]
	global_atomic_add_f32 v232, v223, s[30:31]
	s_or_b64 exec, exec, s[48:49]
	ds_bpermute_b32 v229, v233, v222
	s_waitcnt vmcnt(23)
	v_pk_fma_f32 v[206:207], v[50:51], v[160:161], v[206:207] op_sel_hi:[1,0,1]
	v_pk_fma_f32 v[204:205], v[48:49], v[160:161], v[204:205] op_sel_hi:[1,0,1]
	v_pk_fma_f32 v[210:211], v[46:47], v[160:161], v[210:211] op_sel_hi:[1,0,1]
	v_pk_fma_f32 v[208:209], v[44:45], v[160:161], v[208:209] op_sel_hi:[1,0,1]
	v_add_u32_e32 v231, 0x48000, v221
	v_cvt_pk_bf16_f32 v48, v204, v205
	v_cvt_pk_bf16_f32 v49, v206, v207
	v_cvt_pk_bf16_f32 v50, v208, v209
	v_cvt_pk_bf16_f32 v51, v210, v211
	global_store_dwordx4 v231, v[48:51], s[12:13]
	v_mul_f32_e32 v223, v204, v204
	v_fmac_f32_e32 v223, v205, v205
	v_fmac_f32_e32 v223, v206, v206
	v_fmac_f32_e32 v223, v207, v207
	v_fmac_f32_e32 v223, v208, v208
	v_fmac_f32_e32 v223, v209, v209
	v_fmac_f32_e32 v223, v210, v210
	v_fmac_f32_e32 v223, v211, v211
	v_lshlrev_b32_e32 v224, 16, v48
	v_and_b32_e32 v225, 0xffff0000, v48
	v_sub_f32_e32 v224, v204, v224
	v_sub_f32_e32 v225, v205, v225
	v_cvt_pk_bf16_f32 v44, v224, v225
	v_lshlrev_b32_e32 v226, 16, v49
	v_and_b32_e32 v227, 0xffff0000, v49
	v_sub_f32_e32 v226, v206, v226
	v_sub_f32_e32 v227, v207, v227
	v_cvt_pk_bf16_f32 v45, v226, v227
	v_lshlrev_b32_e32 v224, 16, v50
	v_and_b32_e32 v225, 0xffff0000, v50
	v_sub_f32_e32 v224, v208, v224
	v_sub_f32_e32 v225, v209, v225
	v_cvt_pk_bf16_f32 v46, v224, v225
	v_lshlrev_b32_e32 v226, 16, v51
	v_and_b32_e32 v227, 0xffff0000, v51
	v_sub_f32_e32 v226, v210, v226
	v_sub_f32_e32 v227, v211, v227
	v_cvt_pk_bf16_f32 v47, v226, v227
	global_store_dwordx4 v231, v[44:47], s[10:11]
	s_waitcnt lgkmcnt(0)
	v_add_f32_e32 v222, v222, v229
	ds_bpermute_b32 v229, v234, v222
	s_waitcnt vmcnt(21)
	v_pk_fma_f32 v[214:215], v[42:43], v[160:161], v[214:215] op_sel_hi:[1,0,1]
	v_pk_fma_f32 v[212:213], v[40:41], v[160:161], v[212:213] op_sel_hi:[1,0,1]
	v_pk_fma_f32 v[218:219], v[38:39], v[160:161], v[218:219] op_sel_hi:[1,0,1]
	v_pk_fma_f32 v[216:217], v[36:37], v[160:161], v[216:217] op_sel_hi:[1,0,1]
	v_cvt_pk_bf16_f32 v40, v212, v213
	v_cvt_pk_bf16_f32 v41, v214, v215
	v_cvt_pk_bf16_f32 v42, v216, v217
	v_cvt_pk_bf16_f32 v43, v218, v219
	global_store_dwordx4 v231, v[40:43], s[12:13] offset:256
	v_fmac_f32_e32 v223, v212, v212
	v_fmac_f32_e32 v223, v213, v213
	v_fmac_f32_e32 v223, v214, v214
	v_fmac_f32_e32 v223, v215, v215
	v_fmac_f32_e32 v223, v216, v216
	v_fmac_f32_e32 v223, v217, v217
	v_fmac_f32_e32 v223, v218, v218
	v_fmac_f32_e32 v223, v219, v219
	v_lshlrev_b32_e32 v224, 16, v40
	v_and_b32_e32 v225, 0xffff0000, v40
	v_sub_f32_e32 v224, v212, v224
	v_sub_f32_e32 v225, v213, v225
	v_cvt_pk_bf16_f32 v36, v224, v225
	v_lshlrev_b32_e32 v226, 16, v41
	v_and_b32_e32 v227, 0xffff0000, v41
	v_sub_f32_e32 v226, v214, v226
	v_sub_f32_e32 v227, v215, v227
	v_cvt_pk_bf16_f32 v37, v226, v227
	v_lshlrev_b32_e32 v224, 16, v42
	v_and_b32_e32 v225, 0xffff0000, v42
	v_sub_f32_e32 v224, v216, v224
	v_sub_f32_e32 v225, v217, v225
	v_cvt_pk_bf16_f32 v38, v224, v225
	v_lshlrev_b32_e32 v226, 16, v43
	v_and_b32_e32 v227, 0xffff0000, v43
	v_sub_f32_e32 v226, v218, v226
	v_sub_f32_e32 v227, v219, v227
	v_cvt_pk_bf16_f32 v39, v226, v227
	global_store_dwordx4 v231, v[36:39], s[10:11] offset:256
	s_waitcnt lgkmcnt(0)
	v_add_f32_e32 v222, v222, v229
	v_add_u32_e32 v232, 0x200, v228
	s_and_saveexec_b64 s[48:49], s[2:3]
	global_atomic_add_f32 v232, v222, s[30:31]
	s_or_b64 exec, exec, s[48:49]
	ds_bpermute_b32 v229, v233, v223
	s_waitcnt vmcnt(19)
; __device__ __forceinline__ unsigned cvt_pk(float lo, float hi) { unsigned r; asm("v_cvt_pk_bf16_f32 %0, %1, %2" : "=v"(r) : "v"(lo), "v"(hi)); return r; }
; __device__ __forceinline__ float bflo(unsigned w) { return __uint_as_float(w << 16); }
; __device__ __forceinline__ float bfhi(unsigned w) { return __uint_as_float(w & 0xffff0000u); }
; __device__ __forceinline__ void fadd_atomic(float* p, float v) { __hip_atomic_fetch_add(p, v, __ATOMIC_RELAXED, __HIP_MEMORY_SCOPE_AGENT); }
;     __device__ __forceinline__ void operator()(const f32x4 (&acc)[2][2][4][2], const Unit& u, int wr, int wc, int fr, int fq) const {
;         int row0 = u.pm * BM + wr * 64 + fr; asm volatile("" : "+v"(row0));
; #pragma unroll
;         for (int ai = 0; ai < 2; ++ai)
; #pragma unroll
;             for (int m = 0; m < 4; ++m) { const int row = row0 + ai * HALF + m * 16; const float rb = pre[ai * 4 + m]; float q = 0.f;
; #pragma unroll
;                 for (int bj = 0; bj < 2; ++bj) { const size_t off = (size_t)row * DM + u.pn * BM + bj * HALF + wc * 32 + 8 * fq;
;                     const f32x4 x0 = *(const f32x4*)(x + off), x1 = *(const f32x4*)(x + off + 4);
;                     const f32x4 h0 = x0 + acc[ai][bj][m][0] * rb, h1 = x1 + acc[ai][bj][m][1] * rb;
;                     u32x4 w; w.x = cvt_pk(h0[0], h0[1]); w.y = cvt_pk(h0[2], h0[3]); w.z = cvt_pk(h1[0], h1[1]); w.w = cvt_pk(h1[2], h1[3]); *(u32x4*)(H1B + off) = w;
;                     u32x4 l; l.x = cvt_pk(h0[0] - bflo(w.x), h0[1] - bfhi(w.x)); l.y = cvt_pk(h0[2] - bflo(w.y), h0[3] - bfhi(w.y)); l.z = cvt_pk(h1[0] - bflo(w.z), h1[1] - bfhi(w.z)); l.w = cvt_pk(h1[2] - bflo(w.w), h1[3] - bfhi(w.w));
;                     *(u32x4*)(LO + off) = l;
;                     q += (h0[0] * h0[0] + h0[1] * h0[1]) + (h0[2] * h0[2] + h0[3] * h0[3]) + (h1[0] * h1[0] + h1[1] * h1[1]) + (h1[2] * h1[2] + h1[3] * h1[3]); }
;                 q += __shfl_xor(q, 16); q += __shfl_xor(q, 32);
;                 if (fq == 0) fadd_atomic(ss2 + row, q);
;                 asm volatile("" ::: "memory"); }
;     }
	v_pk_fma_f32 v[174:175], v[34:35], v[162:163], v[174:175] op_sel_hi:[1,0,1]
	v_pk_fma_f32 v[172:173], v[32:33], v[162:163], v[172:173] op_sel_hi:[1,0,1]
	v_pk_fma_f32 v[178:179], v[30:31], v[162:163], v[178:179] op_sel_hi:[1,0,1]
	v_pk_fma_f32 v[176:177], v[28:29], v[162:163], v[176:177] op_sel_hi:[1,0,1]
	v_add_u32_e32 v231, 0x50000, v221
	v_cvt_pk_bf16_f32 v32, v172, v173
	v_cvt_pk_bf16_f32 v33, v174, v175
	v_cvt_pk_bf16_f32 v34, v176, v177
	v_cvt_pk_bf16_f32 v35, v178, v179
	global_store_dwordx4 v231, v[32:35], s[12:13]
	v_mul_f32_e32 v222, v172, v172
	v_fmac_f32_e32 v222, v173, v173
	v_fmac_f32_e32 v222, v174, v174
	v_fmac_f32_e32 v222, v175, v175
	v_fmac_f32_e32 v222, v176, v176
	v_fmac_f32_e32 v222, v177, v177
	v_fmac_f32_e32 v222, v178, v178
	v_fmac_f32_e32 v222, v179, v179
	v_lshlrev_b32_e32 v224, 16, v32
	v_and_b32_e32 v225, 0xffff0000, v32
	v_sub_f32_e32 v224, v172, v224
	v_sub_f32_e32 v225, v173, v225
	v_cvt_pk_bf16_f32 v28, v224, v225
	v_lshlrev_b32_e32 v226, 16, v33
	v_and_b32_e32 v227, 0xffff0000, v33
	v_sub_f32_e32 v226, v174, v226
	v_sub_f32_e32 v227, v175, v227
	v_cvt_pk_bf16_f32 v29, v226, v227
	v_lshlrev_b32_e32 v224, 16, v34
	v_and_b32_e32 v225, 0xffff0000, v34
	v_sub_f32_e32 v224, v176, v224
	v_sub_f32_e32 v225, v177, v225
	v_cvt_pk_bf16_f32 v30, v224, v225
	v_lshlrev_b32_e32 v226, 16, v35
	v_and_b32_e32 v227, 0xffff0000, v35
	v_sub_f32_e32 v226, v178, v226
	v_sub_f32_e32 v227, v179, v227
	v_cvt_pk_bf16_f32 v31, v226, v227
	global_store_dwordx4 v231, v[28:31], s[10:11]
	s_waitcnt lgkmcnt(0)
	v_add_f32_e32 v223, v223, v229
	ds_bpermute_b32 v229, v234, v223
	s_waitcnt vmcnt(17)
	v_pk_fma_f32 v[182:183], v[26:27], v[162:163], v[182:183] op_sel_hi:[1,0,1]
	v_pk_fma_f32 v[180:181], v[24:25], v[162:163], v[180:181] op_sel_hi:[1,0,1]
	v_pk_fma_f32 v[186:187], v[22:23], v[162:163], v[186:187] op_sel_hi:[1,0,1]
	v_pk_fma_f32 v[184:185], v[20:21], v[162:163], v[184:185] op_sel_hi:[1,0,1]
	v_cvt_pk_bf16_f32 v24, v180, v181
	v_cvt_pk_bf16_f32 v25, v182, v183
	v_cvt_pk_bf16_f32 v26, v184, v185
	v_cvt_pk_bf16_f32 v27, v186, v187
	global_store_dwordx4 v231, v[24:27], s[12:13] offset:256
	v_fmac_f32_e32 v222, v180, v180
	v_fmac_f32_e32 v222, v181, v181
	v_fmac_f32_e32 v222, v182, v182
	v_fmac_f32_e32 v222, v183, v183
	v_fmac_f32_e32 v222, v184, v184
	v_fmac_f32_e32 v222, v185, v185
	v_fmac_f32_e32 v222, v186, v186
	v_fmac_f32_e32 v222, v187, v187
	v_lshlrev_b32_e32 v224, 16, v24
	v_and_b32_e32 v225, 0xffff0000, v24
	v_sub_f32_e32 v224, v180, v224
	v_sub_f32_e32 v225, v181, v225
	v_cvt_pk_bf16_f32 v20, v224, v225
	v_lshlrev_b32_e32 v226, 16, v25
	v_and_b32_e32 v227, 0xffff0000, v25
	v_sub_f32_e32 v226, v182, v226
	v_sub_f32_e32 v227, v183, v227
	v_cvt_pk_bf16_f32 v21, v226, v227
	v_lshlrev_b32_e32 v224, 16, v26
	v_and_b32_e32 v225, 0xffff0000, v26
	v_sub_f32_e32 v224, v184, v224
	v_sub_f32_e32 v225, v185, v225
	v_cvt_pk_bf16_f32 v22, v224, v225
	v_lshlrev_b32_e32 v226, 16, v27
	v_and_b32_e32 v227, 0xffff0000, v27
	v_sub_f32_e32 v226, v186, v226
	v_sub_f32_e32 v227, v187, v227
	v_cvt_pk_bf16_f32 v23, v226, v227
	global_store_dwordx4 v231, v[20:23], s[10:11] offset:256
	s_waitcnt lgkmcnt(0)
	v_add_f32_e32 v223, v223, v229
	v_add_u32_e32 v232, 0x240, v228
	s_and_saveexec_b64 s[48:49], s[2:3]
	global_atomic_add_f32 v232, v223, s[30:31]
	s_or_b64 exec, exec, s[48:49]
	ds_bpermute_b32 v229, v233, v222
	s_waitcnt vmcnt(15)
; __device__ __forceinline__ unsigned cvt_pk(float lo, float hi) { unsigned r; asm("v_cvt_pk_bf16_f32 %0, %1, %2" : "=v"(r) : "v"(lo), "v"(hi)); return r; }
; __device__ __forceinline__ float bflo(unsigned w) { return __uint_as_float(w << 16); }
; __device__ __forceinline__ float bfhi(unsigned w) { return __uint_as_float(w & 0xffff0000u); }
; __device__ __forceinline__ void fadd_atomic(float* p, float v) { __hip_atomic_fetch_add(p, v, __ATOMIC_RELAXED, __HIP_MEMORY_SCOPE_AGENT); }
;     __device__ __forceinline__ void operator()(const f32x4 (&acc)[2][2][4][2], const Unit& u, int wr, int wc, int fr, int fq) const {
;         int row0 = u.pm * BM + wr * 64 + fr; asm volatile("" : "+v"(row0));
; #pragma unroll
;         for (int ai = 0; ai < 2; ++ai)
; #pragma unroll
;             for (int m = 0; m < 4; ++m) { const int row = row0 + ai * HALF + m * 16; const float rb = pre[ai * 4 + m]; float q = 0.f;
; #pragma unroll
;                 for (int bj = 0; bj < 2; ++bj) { const size_t off = (size_t)row * DM + u.pn * BM + bj * HALF + wc * 32 + 8 * fq;
;                     const f32x4 x0 = *(const f32x4*)(x + off), x1 = *(const f32x4*)(x + off + 4);
;                     const f32x4 h0 = x0 + acc[ai][bj][m][0] * rb, h1 = x1 + acc[ai][bj][m][1] * rb;
;                     u32x4 w; w.x = cvt_pk(h0[0], h0[1]); w.y = cvt_pk(h0[2], h0[3]); w.z = cvt_pk(h1[0], h1[1]); w.w = cvt_pk(h1[2], h1[3]); *(u32x4*)(H1B + off) = w;
;                     u32x4 l; l.x = cvt_pk(h0[0] - bflo(w.x), h0[1] - bfhi(w.x)); l.y = cvt_pk(h0[2] - bflo(w.y), h0[3] - bfhi(w.y)); l.z = cvt_pk(h1[0] - bflo(w.z), h1[1] - bfhi(w.z)); l.w = cvt_pk(h1[2] - bflo(w.w), h1[3] - bfhi(w.w));
;                     *(u32x4*)(LO + off) = l;
;                     q += (h0[0] * h0[0] + h0[1] * h0[1]) + (h0[2] * h0[2] + h0[3] * h0[3]) + (h1[0] * h1[0] + h1[1] * h1[1]) + (h1[2] * h1[2] + h1[3] * h1[3]); }
;                 q += __shfl_xor(q, 16); q += __shfl_xor(q, 32);
;                 if (fq == 0) fadd_atomic(ss2 + row, q);
;                 asm volatile("" ::: "memory"); }
;     }
	v_pk_fma_f32 v[190:191], v[18:19], v[164:165], v[190:191] op_sel_hi:[1,0,1]
	v_pk_fma_f32 v[188:189], v[16:17], v[164:165], v[188:189] op_sel_hi:[1,0,1]
	v_pk_fma_f32 v[194:195], v[14:15], v[164:165], v[194:195] op_sel_hi:[1,0,1]
	v_pk_fma_f32 v[192:193], v[12:13], v[164:165], v[192:193] op_sel_hi:[1,0,1]
	v_add_u32_e32 v231, 0x58000, v221
	v_cvt_pk_bf16_f32 v16, v188, v189
	v_cvt_pk_bf16_f32 v17, v190, v191
	v_cvt_pk_bf16_f32 v18, v192, v193
	v_cvt_pk_bf16_f32 v19, v194, v195
	global_store_dwordx4 v231, v[16:19], s[12:13]
	v_mul_f32_e32 v223, v188, v188
	v_fmac_f32_e32 v223, v189, v189
	v_fmac_f32_e32 v223, v190, v190
	v_fmac_f32_e32 v223, v191, v191
	v_fmac_f32_e32 v223, v192, v192
	v_fmac_f32_e32 v223, v193, v193
	v_fmac_f32_e32 v223, v194, v194
	v_fmac_f32_e32 v223, v195, v195
	v_lshlrev_b32_e32 v224, 16, v16
	v_and_b32_e32 v225, 0xffff0000, v16
	v_sub_f32_e32 v224, v188, v224
	v_sub_f32_e32 v225, v189, v225
	v_cvt_pk_bf16_f32 v12, v224, v225
	v_lshlrev_b32_e32 v226, 16, v17
	v_and_b32_e32 v227, 0xffff0000, v17
	v_sub_f32_e32 v226, v190, v226
	v_sub_f32_e32 v227, v191, v227
	v_cvt_pk_bf16_f32 v13, v226, v227
	v_lshlrev_b32_e32 v224, 16, v18
	v_and_b32_e32 v225, 0xffff0000, v18
	v_sub_f32_e32 v224, v192, v224
	v_sub_f32_e32 v225, v193, v225
	v_cvt_pk_bf16_f32 v14, v224, v225
	v_lshlrev_b32_e32 v226, 16, v19
	v_and_b32_e32 v227, 0xffff0000, v19
	v_sub_f32_e32 v226, v194, v226
	v_sub_f32_e32 v227, v195, v227
	v_cvt_pk_bf16_f32 v15, v226, v227
	global_store_dwordx4 v231, v[12:15], s[10:11]
	s_waitcnt lgkmcnt(0)
	v_add_f32_e32 v222, v222, v229
	ds_bpermute_b32 v229, v234, v222
	s_waitcnt vmcnt(13)
	v_pk_fma_f32 v[198:199], v[10:11], v[164:165], v[198:199] op_sel_hi:[1,0,1]
	v_pk_fma_f32 v[196:197], v[8:9], v[164:165], v[196:197] op_sel_hi:[1,0,1]
	v_pk_fma_f32 v[202:203], v[6:7], v[164:165], v[202:203] op_sel_hi:[1,0,1]
	v_pk_fma_f32 v[200:201], v[4:5], v[164:165], v[200:201] op_sel_hi:[1,0,1]
	v_cvt_pk_bf16_f32 v8, v196, v197
	v_cvt_pk_bf16_f32 v9, v198, v199
	v_cvt_pk_bf16_f32 v10, v200, v201
	v_cvt_pk_bf16_f32 v11, v202, v203
	global_store_dwordx4 v231, v[8:11], s[12:13] offset:256
	v_fmac_f32_e32 v223, v196, v196
	v_fmac_f32_e32 v223, v197, v197
	v_fmac_f32_e32 v223, v198, v198
	v_fmac_f32_e32 v223, v199, v199
	v_fmac_f32_e32 v223, v200, v200
	v_fmac_f32_e32 v223, v201, v201
	v_fmac_f32_e32 v223, v202, v202
	v_fmac_f32_e32 v223, v203, v203
	v_lshlrev_b32_e32 v224, 16, v8
	v_and_b32_e32 v225, 0xffff0000, v8
	v_sub_f32_e32 v224, v196, v224
	v_sub_f32_e32 v225, v197, v225
	v_cvt_pk_bf16_f32 v4, v224, v225
	v_lshlrev_b32_e32 v226, 16, v9
	v_and_b32_e32 v227, 0xffff0000, v9
	v_sub_f32_e32 v226, v198, v226
	v_sub_f32_e32 v227, v199, v227
	v_cvt_pk_bf16_f32 v5, v226, v227
	v_lshlrev_b32_e32 v224, 16, v10
	v_and_b32_e32 v225, 0xffff0000, v10
	v_sub_f32_e32 v224, v200, v224
	v_sub_f32_e32 v225, v201, v225
	v_cvt_pk_bf16_f32 v6, v224, v225
	v_lshlrev_b32_e32 v226, 16, v11
	v_and_b32_e32 v227, 0xffff0000, v11
	v_sub_f32_e32 v226, v202, v226
	v_sub_f32_e32 v227, v203, v227
	v_cvt_pk_bf16_f32 v7, v226, v227
	global_store_dwordx4 v231, v[4:7], s[10:11] offset:256
	s_waitcnt lgkmcnt(0)
	v_add_f32_e32 v222, v222, v229
	v_add_u32_e32 v232, 0x280, v228
	s_and_saveexec_b64 s[48:49], s[2:3]
	global_atomic_add_f32 v232, v222, s[30:31]
	s_or_b64 exec, exec, s[48:49]
	ds_bpermute_b32 v229, v233, v223
	s_waitcnt lgkmcnt(0)
	v_add_f32_e32 v223, v223, v229
	ds_bpermute_b32 v229, v234, v223
	s_waitcnt lgkmcnt(0)
	v_add_f32_e32 v223, v223, v229
	v_add_u32_e32 v232, 0x2c0, v228
	s_and_saveexec_b64 s[48:49], s[2:3]
	global_atomic_add_f32 v232, v223, s[30:31]
	s_or_b64 exec, exec, s[48:49]
	s_andn2_b64 vcc, exec, s[4:5]
	s_mov_b64 s[4:5], -1
	s_cbranch_vccnz .LBB0_843
	s_andn2_b64 vcc, exec, s[8:9]
	s_cbranch_vccnz .LBB0_842
	s_barrier
	s_branch .LBB0_842
